# in-proj tile order: odd rounds swap the column halves between even and odd workgroups so every workgroup gets the same mix of epilogue kinds
# speedup vs baseline: 1.0172x; 1.0008x over previous
.LBB0_134:
	s_ashr_i32 s22, s38, 3
	s_add_i32 s22, s48, s22
	s_bfe_u32 s84, s22, 0x10005
	s_lshl_b32 s84, s84, 8
	s_xor_b32 s22, s22, s84
	s_ashr_i32 s23, s22, 31
	s_lshr_b32 s23, s23, 23
	s_add_i32 s23, s22, s23
	s_ashr_i32 s38, s23, 9
	s_lshl_b32 s38, s38, 3
	s_sub_i32 s39, 32, s38
	s_min_i32 s39, s39, 8
	s_abs_i32 s48, s39
	v_cvt_f32_u32_e32 v0, s48
	s_sub_i32 s50, 0, s48
	s_and_b32 s23, s23, 0xfffffe00
	s_sub_i32 s22, s22, s23
	v_rcp_iflag_f32_e32 v0, v0
	s_abs_i32 s23, s22
	s_xor_b32 s49, s22, s39
	s_ashr_i32 s49, s49, 31
	v_mul_f32_e32 v0, 0x4f7ffffe, v0
	v_cvt_u32_f32_e32 v0, v0
	s_nop 0
	v_readfirstlane_b32 s51, v0
	s_mul_i32 s50, s50, s51
	s_mul_hi_u32 s50, s51, s50
	s_add_i32 s51, s51, s50
	s_mul_hi_u32 s50, s23, s51
	s_mul_i32 s51, s50, s48
	s_sub_i32 s23, s23, s51
	s_add_i32 s52, s50, 1
	s_sub_i32 s51, s23, s48
	s_cmp_ge_u32 s23, s48
	s_cselect_b32 s50, s52, s50
	s_cselect_b32 s23, s51, s23
	s_add_i32 s51, s50, 1
	s_cmp_ge_u32 s23, s48
	s_cselect_b32 s23, s51, s50
	s_xor_b32 s23, s23, s49
	s_sub_i32 s48, s23, s49
	s_mul_i32 s23, s48, s39
	s_sub_i32 s22, s22, s23
	s_add_i32 s68, s38, s22
